# elementwise phases P3 and P9: waves 1-7 fetch the per-column parameter vectors once per workgroup into LDS while thread 0 runs the preceding grid barrier, all waves read them back after it (was 20/28
# speedup vs baseline: 1.0006x; 1.0006x over previous
; __device__ __forceinline__ void xcd_barrier(const XcdBarrier& b) {
;     asm volatile("s_waitcnt vmcnt(0)" ::: "memory");
;     __syncthreads();
;     if (threadIdx.x == 0) {
;         unsigned* bar = b.bar;
;         __builtin_amdgcn_s_waitcnt(0);
;         unsigned nloc = b.st[0], nx = b.st[1];
;         if (nloc == 0u) { xcd_barrier_complete(bar, b.x, nloc, nx); b.st[0] = nloc; b.st[1] = nx; }
; __global__ void __launch_bounds__(NTHREADS) fwd_megakernel(Args a) {
;     ...
;         const float* md = mods + ((bx & 7) >> 2) * NMOD;
;         const PVec g1 = pmul(load_pvec(md + 2 * DM, lane), load_pvec(a.f1_post, lane));
;         const PVec gs = pmul1p(load_pvec(a.mix_pre, lane), load_pvec(md + 4 * DM, lane)), sh = load_pvec(md + 3 * DM, lane);
.LBB0_371:
	s_waitcnt vmcnt(0)
	s_waitcnt vmcnt(0)
	s_barrier
	s_cmp_lg_u64 s[92:93], 0
	s_cbranch_scc1 .Lpvpre_p3
	s_cmp_lt_u32 s20, 16
	s_cbranch_scc1 .Lpvpre_p3
	v_readfirstlane_b32 s98, v160
	s_nop 3
	s_lshr_b32 s98, s98, 6
	s_add_i32 s98, s98, -1
	v_readlane_b32 s0, v238, 28
	v_mov_b32_e32 v165, 0
	v_readlane_b32 s1, v238, 29
	s_mov_b64 s[6:7], 0x4000
	s_movk_i32 s5, 0x3000
	v_lshl_add_u64 v[0:1], s[0:1], 0, v[164:165]
	s_mov_b64 s[0:1], 0x2000
	v_lshl_add_u64 v[2:3], v[0:1], 0, s[0:1]
	s_movk_i32 s0, 0x4000
	v_add_co_u32_e64 v6, s[0:1], s0, v0
	s_cmp_lg_u32 s98, 0
	s_cbranch_scc1 .Lpv_p3_0
	global_load_dwordx4 v[176:179], v[2:3], off offset:1024
.Lpv_p3_0:
	s_cmp_lg_u32 s98, 1
	s_cbranch_scc1 .Lpv_p3_1
	global_load_dwordx4 v[176:179], v[2:3], off offset:2048
.Lpv_p3_1:
	s_cmp_lg_u32 s98, 2
	s_cbranch_scc1 .Lpv_p3_2
	global_load_dwordx4 v[176:179], v164, s[50:51]
.Lpv_p3_2:
	s_cmp_lg_u32 s98, 3
	s_cbranch_scc1 .Lpv_p3_3
	global_load_dwordx4 v[176:179], v164, s[50:51] offset:1024
.Lpv_p3_3:
	s_cmp_lg_u32 s98, 4
	s_cbranch_scc1 .Lpv_p3_4
	global_load_dwordx4 v[176:179], v164, s[50:51] offset:2048
.Lpv_p3_4:
	v_addc_co_u32_e64 v7, s[0:1], 0, v1, s[0:1]
	s_cmp_lg_u32 s98, 5
	s_cbranch_scc1 .Lpv_p3_5
	global_load_dwordx4 v[176:179], v[6:7], off
.Lpv_p3_5:
	v_lshl_add_u64 v[6:7], v[0:1], 0, s[6:7]
	s_cmp_lg_u32 s98, 6
	s_cbranch_scc1 .Lpv_p3_6
	global_load_dwordx4 v[176:179], v[6:7], off offset:1024
.Lpv_p3_6:
	s_cmp_lg_u32 s98, 0
	s_cbranch_scc1 .Lpv_p3_7
	global_load_dwordx4 v[180:183], v[6:7], off offset:2048
.Lpv_p3_7:
	s_cmp_lg_u32 s98, 1
	s_cbranch_scc1 .Lpv_p3_8
	global_load_dwordx4 v[180:183], v[6:7], off offset:3072
.Lpv_p3_8:
	v_add_co_u32_e32 v4, vcc, 0x2000, v0
	s_mov_b64 s[0:1], 0x3000
	s_nop 0
	v_addc_co_u32_e32 v5, vcc, 0, v1, vcc
	v_add_co_u32_e32 v8, vcc, s5, v0
	v_lshl_add_u64 v[12:13], v[0:1], 0, s[0:1]
	s_nop 0
	v_addc_co_u32_e32 v9, vcc, 0, v1, vcc
	s_cmp_lg_u32 s98, 2
	s_cbranch_scc1 .Lpv_p3_9
	global_load_dwordx4 v[180:183], v[4:5], off
.Lpv_p3_9:
	s_cmp_lg_u32 s98, 3
	s_cbranch_scc1 .Lpv_p3_10
	global_load_dwordx4 v[180:183], v[2:3], off offset:3072
.Lpv_p3_10:
	s_cmp_lg_u32 s98, 4
	s_cbranch_scc1 .Lpv_p3_11
	global_load_dwordx4 v[180:183], v164, s[50:51] offset:3072
.Lpv_p3_11:
	s_cmp_lg_u32 s98, 5
	s_cbranch_scc1 .Lpv_p3_12
	global_load_dwordx4 v[180:183], v164, s[74:75]
.Lpv_p3_12:
	s_cmp_lg_u32 s98, 6
	s_cbranch_scc1 .Lpv_p3_13
	global_load_dwordx4 v[180:183], v164, s[74:75] offset:1024
.Lpv_p3_13:
	s_cmp_lg_u32 s98, 0
	s_cbranch_scc1 .Lpv_p3_14
	global_load_dwordx4 v[184:187], v164, s[74:75] offset:2048
.Lpv_p3_14:
	s_cmp_lg_u32 s98, 1
	s_cbranch_scc1 .Lpv_p3_15
	global_load_dwordx4 v[184:187], v164, s[74:75] offset:3072
.Lpv_p3_15:
	s_cmp_lg_u32 s98, 2
	s_cbranch_scc1 .Lpv_p3_16
	global_load_dwordx4 v[184:187], v[12:13], off offset:1024
.Lpv_p3_16:
	s_cmp_lg_u32 s98, 3
	s_cbranch_scc1 .Lpv_p3_17
	global_load_dwordx4 v[184:187], v[12:13], off offset:2048
.Lpv_p3_17:
	s_nop 0
	s_cmp_lg_u32 s98, 4
	s_cbranch_scc1 .Lpv_p3_18
	global_load_dwordx4 v[184:187], v[8:9], off
.Lpv_p3_18:
	s_nop 0
	s_cmp_lg_u32 s98, 5
	s_cbranch_scc1 .Lpv_p3_19
	global_load_dwordx4 v[184:187], v[12:13], off offset:3072
.Lpv_p3_19:
	s_lshl_b32 s98, s98, 10
	s_nop 0
	v_add_u32_e32 v192, s98, v164
	s_waitcnt vmcnt(0)
	ds_write_b128 v192, v[176:179]
	ds_write_b128 v192, v[180:183] offset:7168
	ds_write_b128 v192, v[184:187] offset:14336
	ds_write_b128 v192, v[188:191] offset:21504
	s_waitcnt lgkmcnt(0)
.Lpvpre_p3:
	s_and_saveexec_b64 s[0:1], s[92:93]
	s_cbranch_execz .LBB0_423
	s_add_i32 s4, 0, 0x23fe0
	v_mov_b32_e32 v0, s4
	s_waitcnt vmcnt(0) expcnt(0) lgkmcnt(0)
	ds_read_b32 v2, v0
	s_add_i32 s4, 0, 0x23fe4
	v_mov_b32_e32 v0, s4
	ds_read_b32 v0, v0
	s_waitcnt lgkmcnt(1)
	v_cmp_ne_u32_e32 vcc, 0, v2
	s_cbranch_vccnz .LBB0_387
	s_add_u32 s4, s30, 0x1000
	s_addc_u32 s5, s31, 0
	s_add_u32 s6, s30, 0x1100
	s_addc_u32 s7, s31, 0
	s_add_u32 s8, s30, 0x1200
	s_addc_u32 s9, s31, 0
	s_mul_i32 s16, s91, s85
	s_add_u32 s10, s30, 0x1300
	s_mul_i32 s16, s16, s90
	s_addc_u32 s11, s31, 0
	s_mov_b32 s18, 1
	v_mov_b32_e32 v16, 0
	s_branch .LBB0_375

; __global__ void __launch_bounds__(NTHREADS) fwd_megakernel(Args a) {
;     ...
;         const float* md = mods + ((bx & 7) >> 2) * NMOD;
;         const PVec g1 = pmul(load_pvec(md + 2 * DM, lane), load_pvec(a.f1_post, lane));
;         const PVec gs = pmul1p(load_pvec(a.mix_pre, lane), load_pvec(md + 4 * DM, lane)), sh = load_pvec(md + 3 * DM, lane);
;         for (int rl = ((bx >> 3) - 2) * NWAVES + wave; rl < 2048; rl += 30 * NWAVES) { const int row = (bx & 7) * 2048 + rl;
;             f32x4 h[4], y[4], o[4]; load_row_f32(a.x + (size_t)row * DM, lane, h); load_row_bf16(Y1 + (size_t)row * DM, lane, y);
;             add_branch_r(h, y, 0.5f, g1);
;             norm_mod_r(h, o, gs, sh);
;             store_row_bf16(R1 + (size_t)row * DM, lane, o);
.LBB0_423:
	s_or_b64 exec, exec, s[0:1]
	s_add_u32 s10, s30, 0x40000
	s_addc_u32 s11, s31, 0
	s_add_u32 s40, s30, 0x9b00000
	s_addc_u32 s41, s31, 0
	s_add_u32 s62, s30, 0xbc00000
	s_addc_u32 s63, s31, 0
	s_cmp_gt_i32 s20, 15
	s_mov_b64 s[0:1], -1
	s_waitcnt lgkmcnt(0)
	s_barrier
	s_cbranch_scc0 .LBB0_428
	v_readlane_b32 s0, v238, 26
	s_add_i32 s4, s0, s21
	s_add_i32 s0, s4, -16
	s_cmpk_gt_i32 s0, 0x7ff
	s_cbranch_scc1 .LBB0_427
	v_readlane_b32 s0, v238, 28
	v_mov_b32_e32 v165, 0
	v_readlane_b32 s1, v238, 29
	s_mov_b64 s[6:7], 0x4000
	s_movk_i32 s5, 0x3000
	v_lshl_add_u64 v[0:1], s[0:1], 0, v[164:165]
	s_mov_b64 s[0:1], 0x2000
	v_lshl_add_u64 v[2:3], v[0:1], 0, s[0:1]
	s_movk_i32 s0, 0x4000
	v_add_co_u32_e64 v6, s[0:1], s0, v0
	v_addc_co_u32_e64 v7, s[0:1], 0, v1, s[0:1]
	v_lshl_add_u64 v[6:7], v[0:1], 0, s[6:7]
	v_add_co_u32_e32 v4, vcc, 0x2000, v0
	s_mov_b64 s[0:1], 0x3000
	s_nop 0
	v_addc_co_u32_e32 v5, vcc, 0, v1, vcc
	v_add_co_u32_e32 v8, vcc, s5, v0
	v_lshl_add_u64 v[12:13], v[0:1], 0, s[0:1]
	s_nop 0
	v_addc_co_u32_e32 v9, vcc, 0, v1, vcc
	s_nop 0
	s_nop 0
	ds_read_b128 v[18:21], v164
	ds_read_b128 v[22:25], v164 offset:1024
	ds_read_b128 v[26:29], v164 offset:2048
	ds_read_b128 v[30:33], v164 offset:3072
	ds_read_b128 v[34:37], v164 offset:4096
	ds_read_b128 v[38:41], v164 offset:5120
	ds_read_b128 v[42:45], v164 offset:6144
	ds_read_b128 v[46:49], v164 offset:7168
	ds_read_b128 v[56:59], v164 offset:8192
	ds_read_b128 v[60:63], v164 offset:9216
	ds_read_b128 v[64:67], v164 offset:10240
	ds_read_b128 v[68:71], v164 offset:11264
	ds_read_b128 v[72:75], v164 offset:12288
	ds_read_b128 v[76:79], v164 offset:13312
	ds_read_b128 v[80:83], v164 offset:14336
	ds_read_b128 v[84:87], v164 offset:15360
	ds_read_b128 v[0:3], v164 offset:16384
	ds_read_b128 v[4:7], v164 offset:17408
	ds_read_b128 v[8:11], v164 offset:18432
	ds_read_b128 v[12:15], v164 offset:19456
	s_waitcnt lgkmcnt(0)
	v_mbcnt_hi_u32_b32 v50, -1, v174
	v_and_b32_e32 v16, 64, v50
	v_xor_b32_e32 v17, 1, v50
	v_add_u32_e32 v88, 64, v16
	v_xor_b32_e32 v51, 2, v50
	v_cmp_lt_i32_e32 vcc, v17, v88
	v_xor_b32_e32 v52, 4, v50
	v_readlane_b32 s0, v238, 27
	v_cndmask_b32_e32 v16, v50, v17, vcc
	v_cmp_lt_i32_e32 vcc, v51, v88
	s_add_i32 s0, s4, s0
	s_add_i32 s0, s0, -16
	v_cndmask_b32_e32 v17, v50, v51, vcc
	v_cmp_lt_i32_e32 vcc, v52, v88
	v_lshlrev_b32_e32 v53, 2, v17
	s_ashr_i32 s1, s0, 31
	v_cndmask_b32_e32 v51, v50, v52, vcc
	v_lshlrev_b32_e32 v52, 2, v16
	s_add_i32 s8, s4, 0xffffff00
	s_lshl_b64 s[4:5], s[0:1], 11
	s_add_u32 s4, s30, s4
	s_addc_u32 s5, s31, s5
	s_lshl_b64 s[0:1], s[0:1], 12
	s_add_u32 s0, s36, s0
	v_mov_b32_e32 v163, v165
	s_addc_u32 s1, s37, s1
	v_lshlrev_b32_e32 v54, 2, v51
	s_mov_b32 s9, 0xf800000
	s_mov_b64 s[6:7], 0xf0000
	s_waitcnt vmcnt(16)
	v_pk_mul_f32 v[16:17], v[20:21], v[32:33]
	s_waitcnt vmcnt(15)
	v_pk_mul_f32 v[22:23], v[22:23], v[34:35]
	v_pk_mul_f32 v[20:21], v[24:25], v[36:37]
	v_pk_mul_f32 v[18:19], v[18:19], v[30:31]
	s_waitcnt vmcnt(14)
	v_pk_add_f32 v[32:33], v[40:41], 1.0 op_sel_hi:[1,0]
	s_waitcnt vmcnt(12)
	v_pk_add_f32 v[40:41], v[48:49], 1.0 op_sel_hi:[1,0]
	v_xor_b32_e32 v48, 8, v50
	v_cmp_lt_i32_e32 vcc, v48, v88
	v_pk_add_f32 v[34:35], v[38:39], 1.0 op_sel_hi:[1,0]
	v_pk_add_f32 v[38:39], v[42:43], 1.0 op_sel_hi:[1,0]
	v_cndmask_b32_e32 v48, v50, v48, vcc
	v_lshlrev_b32_e32 v55, 2, v48
	v_xor_b32_e32 v48, 16, v50
	v_cmp_lt_i32_e32 vcc, v48, v88
	v_pk_add_f32 v[42:43], v[46:47], 1.0 op_sel_hi:[1,0]
	s_waitcnt vmcnt(11)
	v_pk_add_f32 v[46:47], v[56:57], 1.0 op_sel_hi:[1,0]
	v_cndmask_b32_e32 v48, v50, v48, vcc
	v_lshlrev_b32_e32 v56, 2, v48
	v_xor_b32_e32 v48, 32, v50
	v_cmp_lt_i32_e32 vcc, v48, v88
	v_mov_b32_e32 v49, v165
	v_pk_add_f32 v[36:37], v[44:45], 1.0 op_sel_hi:[1,0]
	v_cndmask_b32_e32 v48, v50, v48, vcc
	v_lshlrev_b32_e32 v57, 2, v48
	v_lshlrev_b32_e32 v48, 3, v161
	v_pk_add_f32 v[44:45], v[58:59], 1.0 op_sel_hi:[1,0]
	v_lshl_add_u64 v[48:49], s[4:5], 0, v[48:49]
	s_mov_b64 s[4:5], 0x5a00600
	v_lshl_add_u64 v[50:51], s[0:1], 0, v[162:163]
	s_mov_b64 s[0:1], 0x800
	s_waitcnt vmcnt(10)
	v_pk_mul_f32 v[24:25], v[62:63], v[28:29]
	v_pk_mul_f32 v[26:27], v[60:61], v[26:27]
	s_waitcnt vmcnt(8)
	v_pk_mul_f32 v[28:29], v[66:67], v[70:71]
	v_pk_mul_f32 v[30:31], v[64:65], v[68:69]
	s_waitcnt vmcnt(7)
	v_pk_mul_f32 v[32:33], v[74:75], v[32:33]
	v_pk_mul_f32 v[34:35], v[72:73], v[34:35]
	s_waitcnt vmcnt(6)
	v_pk_mul_f32 v[36:37], v[78:79], v[36:37]
	v_pk_mul_f32 v[38:39], v[76:77], v[38:39]
	s_waitcnt vmcnt(5)
	v_pk_mul_f32 v[40:41], v[82:83], v[40:41]
	v_pk_mul_f32 v[42:43], v[80:81], v[42:43]
	s_waitcnt vmcnt(4)
	v_pk_mul_f32 v[44:45], v[86:87], v[44:45]
	v_pk_mul_f32 v[46:47], v[84:85], v[46:47]
	v_lshl_add_u64 v[48:49], v[48:49], 0, s[4:5]
	v_lshl_add_u64 v[50:51], v[50:51], 0, s[0:1]
	v_mov_b32_e32 v58, 0x358637bd
	v_mov_b32_e32 v59, 0x260
	s_mov_b64 s[4:5], 0x78000

; __device__ __forceinline__ void xcd_barrier(const XcdBarrier& b) {
;     asm volatile("s_waitcnt vmcnt(0)" ::: "memory");
;     __syncthreads();
;     if (threadIdx.x == 0) {
; __global__ void __launch_bounds__(NTHREADS) fwd_megakernel(Args a) {
;     ...
;     { const float* md = mods + ((bx & 7) >> 2) * NMOD;
;       const PVec g1 = pmul(load_pvec(md + 2 * DM, lane), load_pvec(a.f1_post, lane)), g2 = pmul(load_pvec(md + 5 * DM, lane), load_pvec(a.mix_post, lane));
;       const PVec gs = pmul1p(load_pvec(a.f2_pre, lane), load_pvec(md + 7 * DM, lane)), sh = load_pvec(md + 6 * DM, lane);
.LBB0_1120:
	s_waitcnt vmcnt(0)
	s_waitcnt vmcnt(0)
	s_barrier
	s_cmp_lg_u64 s[92:93], 0
	s_cbranch_scc1 .Lpvpre_p9
	v_readfirstlane_b32 s98, v160
	s_nop 3
	s_lshr_b32 s98, s98, 6
	s_add_i32 s98, s98, -1
	v_readlane_b32 s6, v238, 28
	v_mov_b32_e32 v165, 0
	v_readlane_b32 s7, v238, 29
	s_movk_i32 s2, 0x6000
	s_ashr_i32 s23, s22, 31
	v_lshl_add_u64 v[0:1], s[6:7], 0, v[164:165]
	s_mov_b64 s[6:7], 0x2000
	v_lshl_add_u64 v[2:3], v[0:1], 0, s[6:7]
	s_mov_b64 s[6:7], 0x5000
	v_lshl_add_u64 v[6:7], v[0:1], 0, s[6:7]
	v_add_co_u32_e64 v32, s[6:7], s2, v0
	s_movk_i32 s2, 0x7000
	s_nop 0
	v_addc_co_u32_e64 v33, s[6:7], 0, v1, s[6:7]
	s_mov_b64 s[6:7], 0x7000
	v_add_co_u32_e32 v4, vcc, 0x2000, v0
	s_cmp_lg_u32 s98, 0
	s_cbranch_scc1 .Lpv_p9_0
	global_load_dwordx4 v[176:179], v[2:3], off offset:1024

; __global__ void __launch_bounds__(NTHREADS) fwd_megakernel(Args a) {
;     ...
;     { const float* md = mods + ((bx & 7) >> 2) * NMOD;
;       const PVec g1 = pmul(load_pvec(md + 2 * DM, lane), load_pvec(a.f1_post, lane)), g2 = pmul(load_pvec(md + 5 * DM, lane), load_pvec(a.mix_post, lane));
;       const PVec gs = pmul1p(load_pvec(a.f2_pre, lane), load_pvec(md + 7 * DM, lane)), sh = load_pvec(md + 6 * DM, lane);
.Lpv_p9_4:
	s_cmp_lg_u32 s98, 5
	s_cbranch_scc1 .Lpv_p9_5
	global_load_dwordx4 v[176:179], v[32:33], off offset:-4096
.Lpv_p9_5:
	s_cmp_lg_u32 s98, 6
	s_cbranch_scc1 .Lpv_p9_6
	global_load_dwordx4 v[176:179], v[6:7], off offset:1024

; __global__ void __launch_bounds__(NTHREADS) fwd_megakernel(Args a) {
;     ...
;     { const float* md = mods + ((bx & 7) >> 2) * NMOD;
;       const PVec g1 = pmul(load_pvec(md + 2 * DM, lane), load_pvec(a.f1_post, lane)), g2 = pmul(load_pvec(md + 5 * DM, lane), load_pvec(a.mix_post, lane));
;       const PVec gs = pmul1p(load_pvec(a.f2_pre, lane), load_pvec(md + 7 * DM, lane)), sh = load_pvec(md + 6 * DM, lane);
.Lpv_p9_8:
	s_cmp_lg_u32 s98, 2
	s_cbranch_scc1 .Lpv_p9_9
	global_load_dwordx4 v[180:183], v164, s[76:77]
.Lpv_p9_9:
	s_cmp_lg_u32 s98, 3
	s_cbranch_scc1 .Lpv_p9_10
	global_load_dwordx4 v[180:183], v164, s[76:77] offset:1024
.Lpv_p9_10:
	s_cmp_lg_u32 s98, 4
	s_cbranch_scc1 .Lpv_p9_11
	global_load_dwordx4 v[180:183], v164, s[76:77] offset:2048
.Lpv_p9_11:
	s_cmp_lg_u32 s98, 5
	s_cbranch_scc1 .Lpv_p9_12
	global_load_dwordx4 v[180:183], v164, s[76:77] offset:3072
.Lpv_p9_12:
	v_lshl_add_u64 v[6:7], v[0:1], 0, s[6:7]
	v_add_co_u32_e64 v8, s[6:7], s2, v0
	v_addc_co_u32_e32 v5, vcc, 0, v1, vcc
	s_nop 0
	v_addc_co_u32_e64 v9, s[6:7], 0, v1, s[6:7]
	s_cmp_lg_u32 s98, 6
	s_cbranch_scc1 .Lpv_p9_13
	global_load_dwordx4 v[180:183], v[8:9], off
.Lpv_p9_13:
	s_cmp_lg_u32 s98, 0
	s_cbranch_scc1 .Lpv_p9_14
	global_load_dwordx4 v[184:187], v[6:7], off offset:1024
.Lpv_p9_14:
	s_cmp_lg_u32 s98, 1
	s_cbranch_scc1 .Lpv_p9_15
	global_load_dwordx4 v[184:187], v[6:7], off offset:2048
.Lpv_p9_15:
	s_cmp_lg_u32 s98, 2
	s_cbranch_scc1 .Lpv_p9_16
	global_load_dwordx4 v[184:187], v[4:5], off
.Lpv_p9_16:
	s_cmp_lg_u32 s98, 3
	s_cbranch_scc1 .Lpv_p9_17
	global_load_dwordx4 v[184:187], v[2:3], off offset:3072
.Lpv_p9_17:
	s_cmp_lg_u32 s98, 4
	s_cbranch_scc1 .Lpv_p9_18
	global_load_dwordx4 v[184:187], v164, s[50:51] offset:3072
.Lpv_p9_18:
	s_cmp_lg_u32 s98, 5
	s_cbranch_scc1 .Lpv_p9_19
	global_load_dwordx4 v[184:187], v164, s[66:67]
.Lpv_p9_19:
	s_cmp_lg_u32 s98, 6
	s_cbranch_scc1 .Lpv_p9_20
	global_load_dwordx4 v[184:187], v164, s[66:67] offset:1024
.Lpv_p9_20:
	s_cmp_lg_u32 s98, 0
	s_cbranch_scc1 .Lpv_p9_21
	global_load_dwordx4 v[188:191], v164, s[66:67] offset:2048
.Lpv_p9_21:
	s_cmp_lg_u32 s98, 1
	s_cbranch_scc1 .Lpv_p9_22
	global_load_dwordx4 v[188:191], v[6:7], off offset:3072
.Lpv_p9_22:
	s_cmp_lg_u32 s98, 2
	s_cbranch_scc1 .Lpv_p9_23
	global_load_dwordx4 v[188:191], v164, s[66:67] offset:3072
.Lpv_p9_23:
	s_mov_b64 s[6:7], 0x6000
	v_lshl_add_u64 v[34:35], v[0:1], 0, s[6:7]
	s_cmp_lg_u32 s98, 3
	s_cbranch_scc1 .Lpv_p9_24
	global_load_dwordx4 v[188:191], v[32:33], off
.Lpv_p9_24:
	s_cmp_lg_u32 s98, 4
	s_cbranch_scc1 .Lpv_p9_25
	global_load_dwordx4 v[188:191], v[34:35], off offset:1024
.Lpv_p9_25:
	s_cmp_lg_u32 s98, 5
	s_cbranch_scc1 .Lpv_p9_26
	global_load_dwordx4 v[188:191], v[34:35], off offset:2048
.Lpv_p9_26:
	s_cmp_lg_u32 s98, 6
	s_cbranch_scc1 .Lpv_p9_27
	global_load_dwordx4 v[188:191], v[34:35], off offset:3072

; __device__ __forceinline__ unsigned xb_ld(unsigned* p)              { return __hip_atomic_load(p, __ATOMIC_RELAXED, __HIP_MEMORY_SCOPE_AGENT); }
; __device__ __forceinline__ void xcd_barrier_complete(unsigned* bar, unsigned x, unsigned& nloc, unsigned& nx) {
;     const unsigned G = gridDim.x * gridDim.y * gridDim.z;
;     unsigned sum, cnt, mine, sp = 0u;
;     for (;;) {
;         sum = 0u; cnt = 0u; mine = 0u;
; #pragma unroll
;         for (unsigned j = 0; j < 16; ++j) { const unsigned c = xb_ld(&bar[XB_XCNT(j)]); sum += c; cnt += (c > 0u) ? 1u : 0u; mine = (j == x) ? c : mine; }
; __device__ __forceinline__ void xcd_barrier(const XcdBarrier& b) {
;     ...
;     if (threadIdx.x == 0) {
;         unsigned* bar = b.bar;
;         __builtin_amdgcn_s_waitcnt(0);
;         unsigned nloc = b.st[0], nx = b.st[1];
;         if (nloc == 0u) { xcd_barrier_complete(bar, b.x, nloc, nx); b.st[0] = nloc; b.st[1] = nx; }
.Lpvpre_p9:
	s_and_saveexec_b64 s[4:5], s[92:93]
	s_cbranch_execz .LBB0_1172
	s_add_i32 s2, 0, 0x23fe0
	v_mov_b32_e32 v0, s2
	s_waitcnt vmcnt(0) expcnt(0) lgkmcnt(0)
	ds_read_b32 v2, v0
	s_add_i32 s2, 0, 0x23fe4
	v_mov_b32_e32 v0, s2
	ds_read_b32 v0, v0
	s_waitcnt lgkmcnt(1)
	v_cmp_ne_u32_e32 vcc, 0, v2
	s_cbranch_vccnz .LBB0_1136
	s_add_u32 s6, s30, 0x1000
	s_addc_u32 s7, s31, 0
	s_add_u32 s8, s30, 0x1100
	s_addc_u32 s9, s31, 0
	s_add_u32 s10, s30, 0x1200
	s_addc_u32 s11, s31, 0
	s_mul_i32 s2, s91, s85
	s_add_u32 s12, s30, 0x1300
	s_mul_i32 s2, s2, s90
	s_addc_u32 s13, s31, 0
	s_mov_b32 s16, 1
	v_mov_b32_e32 v16, 0
	s_branch .LBB0_1124

; __global__ void __launch_bounds__(NTHREADS) fwd_megakernel(Args a) {
;     ...
;     { const float* md = mods + ((bx & 7) >> 2) * NMOD;
;       const PVec g1 = pmul(load_pvec(md + 2 * DM, lane), load_pvec(a.f1_post, lane)), g2 = pmul(load_pvec(md + 5 * DM, lane), load_pvec(a.mix_post, lane));
;       const PVec gs = pmul1p(load_pvec(a.f2_pre, lane), load_pvec(md + 7 * DM, lane)), sh = load_pvec(md + 6 * DM, lane);
;       for (int row = xrow0; row < xrow1; row += 256) {
;         f32x4 h[4], y[4], y2[4], o[4]; load_row_f32(a.x + (size_t)row * DM, lane, h); load_row_bf16(Y1 + (size_t)row * DM, lane, y); load_row_bf16(Y2 + (size_t)row * DM, lane, y2);
;         add_branch_r(h, y, 0.5f, g1);
;         add_branch_r(h, y2, 1.0f, g2);
;         store_row_f32(a.out + (size_t)row * DM, lane, h);
;         norm_mod_r(h, o, gs, sh);
.LBB0_1172:
	s_or_b64 exec, exec, s[4:5]
	s_waitcnt lgkmcnt(0)
	v_cndmask_b32_e64 v0, 0, 1, s[86:87]
	v_cmp_ne_u32_e64 s[4:5], 1, v0
	s_andn2_b64 vcc, exec, s[86:87]
	s_barrier
	s_cbranch_vccnz .LBB0_1175
	v_readlane_b32 s6, v238, 28
	v_mov_b32_e32 v165, 0
	v_readlane_b32 s7, v238, 29
	s_movk_i32 s2, 0x6000
	s_ashr_i32 s23, s22, 31
	v_lshl_add_u64 v[0:1], s[6:7], 0, v[164:165]
	s_mov_b64 s[6:7], 0x2000
	v_lshl_add_u64 v[2:3], v[0:1], 0, s[6:7]
	s_mov_b64 s[6:7], 0x5000
	v_lshl_add_u64 v[6:7], v[0:1], 0, s[6:7]
	v_add_co_u32_e64 v32, s[6:7], s2, v0
	s_movk_i32 s2, 0x7000
	s_nop 0
	v_addc_co_u32_e64 v33, s[6:7], 0, v1, s[6:7]
	s_mov_b64 s[6:7], 0x7000
	v_add_co_u32_e32 v4, vcc, 0x2000, v0
	v_lshl_add_u64 v[6:7], v[0:1], 0, s[6:7]
	v_add_co_u32_e64 v8, s[6:7], s2, v0
	v_addc_co_u32_e32 v5, vcc, 0, v1, vcc
	s_nop 0
	v_addc_co_u32_e64 v9, s[6:7], 0, v1, s[6:7]
	s_mov_b64 s[6:7], 0x6000
	v_lshl_add_u64 v[34:35], v[0:1], 0, s[6:7]
	ds_read_b128 v[16:19], v164
	ds_read_b128 v[20:23], v164 offset:1024
	ds_read_b128 v[24:27], v164 offset:2048
	ds_read_b128 v[28:31], v164 offset:3072
	ds_read_b128 v[38:41], v164 offset:4096
	ds_read_b128 v[42:45], v164 offset:5120
	ds_read_b128 v[46:49], v164 offset:6144
	ds_read_b128 v[50:53], v164 offset:7168
	ds_read_b128 v[54:57], v164 offset:8192
	ds_read_b128 v[58:61], v164 offset:9216
	ds_read_b128 v[62:65], v164 offset:10240
	ds_read_b128 v[66:69], v164 offset:11264
	ds_read_b128 v[70:73], v164 offset:12288
	ds_read_b128 v[74:77], v164 offset:13312
	ds_read_b128 v[78:81], v164 offset:14336
	ds_read_b128 v[82:85], v164 offset:15360
	ds_read_b128 v[86:89], v164 offset:16384
	ds_read_b128 v[90:93], v164 offset:17408
	ds_read_b128 v[94:97], v164 offset:18432
	ds_read_b128 v[98:101], v164 offset:19456
	ds_read_b128 v[102:105], v164 offset:20480
	ds_read_b128 v[106:109], v164 offset:21504
	ds_read_b128 v[110:113], v164 offset:22528
	ds_read_b128 v[114:117], v164 offset:23552
	ds_read_b128 v[0:3], v164 offset:24576
	ds_read_b128 v[4:7], v164 offset:25600
	ds_read_b128 v[8:11], v164 offset:26624
	ds_read_b128 v[12:15], v164 offset:27648
	s_waitcnt lgkmcnt(0)
	s_lshl_b64 s[6:7], s[22:23], 11
	s_add_u32 s6, s30, s6
	s_addc_u32 s7, s31, s7
	s_mov_b32 s2, 0x4100000
	s_mov_b32 s12, 0xf800000
	s_mov_b64 s[8:9], 0x80000
	s_mov_b64 s[10:11], 0x100000
	s_mov_b32 s13, s22
	s_waitcnt vmcnt(18)
	v_pk_mul_f32 v[42:43], v[42:43], v[58:59]
	v_pk_mul_f32 v[34:35], v[16:17], v[28:29]
	v_pk_mul_f32 v[36:37], v[22:23], v[40:41]
	v_pk_mul_f32 v[40:41], v[44:45], v[60:61]
	s_waitcnt vmcnt(17)
	v_pk_mul_f32 v[44:45], v[48:49], v[64:65]
	v_pk_mul_f32 v[32:33], v[18:19], v[30:31]
	s_waitcnt vmcnt(16)
	v_pk_mul_f32 v[50:51], v[50:51], v[66:67]
	s_waitcnt vmcnt(9)
	v_pk_mul_f32 v[60:61], v[92:93], v[96:97]
	v_pk_mul_f32 v[46:47], v[46:47], v[62:63]
	v_pk_add_f32 v[16:17], v[76:77], 1.0 op_sel_hi:[1,0]
	v_pk_add_f32 v[18:19], v[74:75], 1.0 op_sel_hi:[1,0]
	s_waitcnt vmcnt(8)
	v_pk_mul_f32 v[64:65], v[100:101], v[16:17]
	s_waitcnt vmcnt(5)
	v_pk_add_f32 v[16:17], v[112:113], 1.0 op_sel_hi:[1,0]
	v_pk_mul_f32 v[66:67], v[98:99], v[18:19]
	s_waitcnt vmcnt(4)
	v_pk_mul_f32 v[76:77], v[116:117], v[16:17]
	v_mbcnt_hi_u32_b32 v16, -1, v174
	v_pk_add_f32 v[18:19], v[110:111], 1.0 op_sel_hi:[1,0]
	v_and_b32_e32 v17, 64, v16
	v_pk_add_f32 v[22:23], v[78:79], 1.0 op_sel_hi:[1,0]
	v_pk_mul_f32 v[78:79], v[114:115], v[18:19]
	v_add_u32_e32 v17, 64, v17
	v_xor_b32_e32 v18, 1, v16
	v_cmp_lt_i32_e32 vcc, v18, v17
	v_pk_mul_f32 v[62:63], v[90:91], v[94:95]
	v_pk_mul_f32 v[38:39], v[20:21], v[38:39]
	v_cndmask_b32_e32 v18, v16, v18, vcc
	v_lshlrev_b32_e32 v92, 2, v18
	v_xor_b32_e32 v18, 2, v16
	v_cmp_lt_i32_e32 vcc, v18, v17
	v_pk_add_f32 v[20:21], v[80:81], 1.0 op_sel_hi:[1,0]
	v_pk_add_f32 v[28:29], v[84:85], 1.0 op_sel_hi:[1,0]
	v_cndmask_b32_e32 v18, v16, v18, vcc
	v_lshlrev_b32_e32 v93, 2, v18
	v_xor_b32_e32 v18, 4, v16
	v_cmp_lt_i32_e32 vcc, v18, v17
	v_pk_add_f32 v[30:31], v[82:83], 1.0 op_sel_hi:[1,0]
	v_pk_mul_f32 v[48:49], v[52:53], v[68:69]
	v_cndmask_b32_e32 v18, v16, v18, vcc
	v_lshlrev_b32_e32 v94, 2, v18
	v_xor_b32_e32 v18, 8, v16
	v_cmp_lt_i32_e32 vcc, v18, v17
	v_pk_mul_f32 v[52:53], v[56:57], v[72:73]
	v_pk_mul_f32 v[54:55], v[54:55], v[70:71]
	v_cndmask_b32_e32 v18, v16, v18, vcc
	v_lshlrev_b32_e32 v95, 2, v18
	v_xor_b32_e32 v18, 16, v16
	v_cmp_lt_i32_e32 vcc, v18, v17
	v_pk_mul_f32 v[56:57], v[88:89], v[26:27]
	v_pk_mul_f32 v[58:59], v[86:87], v[24:25]
	v_cndmask_b32_e32 v18, v16, v18, vcc
	v_lshlrev_b32_e32 v96, 2, v18
	v_xor_b32_e32 v18, 32, v16
	v_cmp_lt_i32_e32 vcc, v18, v17
	v_mov_b32_e32 v17, v165
	v_pk_mul_f32 v[68:69], v[104:105], v[20:21]
	v_cndmask_b32_e32 v16, v16, v18, vcc
	v_lshlrev_b32_e32 v97, 2, v16
	v_lshlrev_b32_e32 v16, 3, v161
	v_lshl_add_u64 v[16:17], s[6:7], 0, v[16:17]
	s_mov_b64 s[6:7], 0x5a00000
	v_lshl_add_u64 v[80:81], v[16:17], 0, s[6:7]
	s_lshl_b64 s[6:7], s[22:23], 12
	v_lshl_or_b32 v16, v161, 4, s6
	v_mov_b32_e32 v17, s7
	v_lshl_add_u64 v[18:19], s[36:37], 0, v[16:17]
	s_mov_b64 s[6:7], 0xc00
	v_lshl_add_u64 v[82:83], v[18:19], 0, s[6:7]
	v_lshl_add_u64 v[16:17], s[28:29], 0, v[16:17]
	s_mov_b64 s[6:7], 0x800
	v_pk_mul_f32 v[70:71], v[102:103], v[22:23]
	v_pk_mul_f32 v[72:73], v[108:109], v[28:29]
	v_pk_mul_f32 v[74:75], v[106:107], v[30:31]
	v_lshl_add_u64 v[84:85], v[16:17], 0, s[6:7]
	v_mov_b32_e32 v98, 0x358637bd
	v_mov_b32_e32 v99, 0x260
